# P6 conv fix-up: the three tasks of a thread software-pipelined (all 42 loads issued before the first compute, counted vmcnt), generic loop kept as fallback
# speedup vs baseline: 1.0188x; 1.0051x over previous
; __device__ __forceinline__ f32x4 raw4(const bf16_t* p) { const u32x2 w = *(const u32x2*)p; return (f32x4){bf_lo(w.x), bf_hi(w.x), bf_lo(w.y), bf_hi(w.y)}; }
; __device__ __forceinline__ void conv_fixup(const bf16_t* RAW, const float* ck, const float* cb, bf16_t* ACT, int gtid, int nthr) {
;     constexpr int NJ = FF / 4, NTASK = 128 * 2 * NJ;
;     for (int task = gtid; task < NTASK; task += nthr) {
;         const int j4 = (task % NJ) * 4, rr = task / NJ, grp = rr >> 1, last = rr & 1;
;         const int row = grp * 64 + (last ? 63 : 0);
;         const f32x4 z = {0.f, 0.f, 0.f, 0.f};
;         f32x4 cv[2];
; #pragma unroll
;         for (int bj = 0; bj < 2; ++bj) {
;             const bf16_t* base = RAW + bj * FF + j4;
;             f32x4 pv, cur, nv;
;             if (!last) { pv = grp > 0 ? raw4(base + (size_t)((grp - 1) * 4 + 3) * NUP) : z; cur = raw4(base + (size_t)(grp * 4 + 0) * NUP); nv = raw4(base + (size_t)(grp * 4 + 1) * NUP); }
;             else { pv = raw4(base + (size_t)(grp * 4 + 2) * NUP); cur = raw4(base + (size_t)(grp * 4 + 3) * NUP); nv = grp < 127 ? raw4(base + (size_t)((grp + 1) * 4 + 0) * NUP) : z; }
;             cv[bj] = *(const f32x4*)(ck + 0 * NUP + bj * FF + j4) * pv + *(const f32x4*)(ck + 1 * NUP + bj * FF + j4) * cur + *(const f32x4*)(ck + 2 * NUP + bj * FF + j4) * nv + *(const f32x4*)(cb + bj * FF + j4);
.LBB0_868:
	s_or_b64 exec, exec, s[0:1]
	v_mov_b32_e32 v0, v240
	v_readlane_b32 s12, v254, 61
	s_waitcnt lgkmcnt(0)
	s_barrier
	s_mov_b64 s[0:1], s[10:11]
	v_add_u32_e32 v64, s12, v0
	s_mov_b32 s12, 0x56000
	v_cmp_gt_i32_e32 vcc, s12, v64
	s_and_saveexec_b64 s[12:13], vcc
	s_cbranch_execz .LBB0_887
	s_add_u32 s16, s0, 0x28200000
	s_addc_u32 s17, s1, 0
	s_add_u32 s30, s0, 0x21800000
	s_addc_u32 s31, s1, 0
	s_add_u32 s34, s18, 0xac00
	s_addc_u32 s35, s19, 0
	s_add_u32 s36, s18, 0x15800
	s_addc_u32 s37, s19, 0
	v_lshlrev_b32_e32 v65, 2, v64
	s_lshl_b32 s22, s80, 2
	s_mov_b64 s[42:43], 0
	v_mov_b32_e32 v65, v64
	v_min_i32_e32 v63, 0x55fff, v65
	s_mov_b32 s0, 0x2fa0be83
	v_mul_hi_i32 v0, v63, s0
	v_lshrrev_b32_e32 v2, 31, v0
	v_ashrrev_i32_e32 v0, 8, v0
	v_add_u32_e32 v0, v0, v2
	v_mul_i32_i24_e32 v2, 0x560, v0
	v_sub_u32_e32 v2, v63, v2
	v_lshlrev_b32_e32 v36, 2, v2
	v_ashrrev_i32_e32 v66, 1, v0
	v_and_b32_e32 v3, 1, v0
	v_lshlrev_b32_e32 v4, 2, v66
	v_mad_u32_u24 v4, v3, 3, v4
	v_mov_b32_e32 v104, v4
	v_add_u32_e32 v5, -1, v4
	v_max_i32_e32 v5, 0, v5
	v_add_u32_e32 v6, 1, v4
	v_min_i32_e32 v6, 0x1ff, v6
	s_movk_i32 s1, 0x5600
	v_lshlrev_b32_e32 v7, 1, v36
	v_mad_u32_u24 v8, v5, s1, v7
	v_mad_u32_u24 v9, v4, s1, v7
	v_mad_u32_u24 v10, v6, s1, v7
	v_add_u32_e32 v11, 0x2b00, v8
	v_add_u32_e32 v22, 0x2b00, v9
	v_add_u32_e32 v23, 0x2b00, v10
	global_load_dwordx2 v[12:13], v8, s[16:17]
	global_load_dwordx2 v[14:15], v9, s[16:17]
	global_load_dwordx2 v[16:17], v10, s[16:17]
	global_load_dwordx2 v[18:19], v11, s[16:17]
	global_load_dwordx2 v[38:39], v22, s[16:17]
	global_load_dwordx2 v[60:61], v23, s[16:17]
	v_lshlrev_b32_e32 v20, 2, v36
	v_add_u32_e32 v21, 0x5600, v20
	global_load_dwordx4 v[24:27], v20, s[18:19]
	global_load_dwordx4 v[28:31], v20, s[34:35]
	global_load_dwordx4 v[32:35], v20, s[36:37]
	global_load_dwordx4 v[40:43], v20, s[20:21]
	global_load_dwordx4 v[44:47], v21, s[18:19]
	global_load_dwordx4 v[48:51], v21, s[34:35]
	global_load_dwordx4 v[52:55], v21, s[36:37]
	global_load_dwordx4 v[56:59], v21, s[20:21]
	v_lshlrev_b32_e32 v67, 6, v66
	v_mad_u32_u24 v67, v3, 63, v67
	v_mad_u32_u24 v107, v67, s7, v7
	v_add_u32_e32 v65, s80, v65
	s_mov_b32 s0, 0x56000
	v_cmp_gt_i32_e64 s[44:45], s0, v65
	v_min_i32_e32 v63, 0x55fff, v65
	s_mov_b32 s0, 0x2fa0be83
	v_mul_hi_i32 v0, v63, s0
	v_lshrrev_b32_e32 v2, 31, v0
	v_ashrrev_i32_e32 v0, 8, v0
	v_add_u32_e32 v0, v0, v2
	v_mul_i32_i24_e32 v2, 0x560, v0
	v_sub_u32_e32 v2, v63, v2
	v_lshlrev_b32_e32 v36, 2, v2
	v_ashrrev_i32_e32 v66, 1, v0
	v_and_b32_e32 v3, 1, v0
	v_lshlrev_b32_e32 v4, 2, v66
	v_mad_u32_u24 v4, v3, 3, v4
	v_mov_b32_e32 v105, v4
	v_add_u32_e32 v5, -1, v4
	v_max_i32_e32 v5, 0, v5
	v_add_u32_e32 v6, 1, v4
	v_min_i32_e32 v6, 0x1ff, v6
	s_movk_i32 s1, 0x5600
	v_lshlrev_b32_e32 v7, 1, v36
	v_mad_u32_u24 v8, v5, s1, v7
	v_mad_u32_u24 v9, v4, s1, v7
	v_mad_u32_u24 v10, v6, s1, v7
	v_add_u32_e32 v11, 0x2b00, v8
	v_add_u32_e32 v22, 0x2b00, v9
	v_add_u32_e32 v23, 0x2b00, v10
	global_load_dwordx2 v[142:143], v8, s[16:17]
	global_load_dwordx2 v[144:145], v9, s[16:17]
	global_load_dwordx2 v[146:147], v10, s[16:17]
	global_load_dwordx2 v[148:149], v11, s[16:17]
	global_load_dwordx2 v[150:151], v22, s[16:17]
	global_load_dwordx2 v[152:153], v23, s[16:17]
	v_lshlrev_b32_e32 v20, 2, v36
	v_add_u32_e32 v21, 0x5600, v20
	global_load_dwordx4 v[174:177], v20, s[18:19]
	global_load_dwordx4 v[178:181], v20, s[34:35]
	global_load_dwordx4 v[182:185], v20, s[36:37]
	global_load_dwordx4 v[186:189], v20, s[20:21]
	global_load_dwordx4 v[190:193], v21, s[18:19]
	global_load_dwordx4 v[194:197], v21, s[34:35]
	global_load_dwordx4 v[198:201], v21, s[36:37]
	global_load_dwordx4 v[202:205], v21, s[20:21]
	v_lshlrev_b32_e32 v67, 6, v66
	v_mad_u32_u24 v67, v3, 63, v67
	v_mad_u32_u24 v108, v67, s7, v7
	v_add_u32_e32 v65, s80, v65
	s_mov_b32 s0, 0x56000
	v_cmp_gt_i32_e64 s[46:47], s0, v65
	v_min_i32_e32 v63, 0x55fff, v65
	s_mov_b32 s0, 0x2fa0be83
	v_mul_hi_i32 v0, v63, s0
	v_lshrrev_b32_e32 v2, 31, v0
	v_ashrrev_i32_e32 v0, 8, v0
	v_add_u32_e32 v0, v0, v2
	v_mul_i32_i24_e32 v2, 0x560, v0
	v_sub_u32_e32 v2, v63, v2
	v_lshlrev_b32_e32 v36, 2, v2
	v_ashrrev_i32_e32 v66, 1, v0
	v_and_b32_e32 v3, 1, v0
	v_lshlrev_b32_e32 v4, 2, v66
	v_mad_u32_u24 v4, v3, 3, v4
	v_mov_b32_e32 v106, v4
	v_add_u32_e32 v5, -1, v4
	v_max_i32_e32 v5, 0, v5
	v_add_u32_e32 v6, 1, v4
	v_min_i32_e32 v6, 0x1ff, v6
	s_movk_i32 s1, 0x5600
	v_lshlrev_b32_e32 v7, 1, v36
	v_mad_u32_u24 v8, v5, s1, v7
	v_mad_u32_u24 v9, v4, s1, v7
	v_mad_u32_u24 v10, v6, s1, v7
	v_add_u32_e32 v11, 0x2b00, v8
	v_add_u32_e32 v22, 0x2b00, v9
	v_add_u32_e32 v23, 0x2b00, v10
	global_load_dwordx2 v[154:155], v8, s[16:17]
	global_load_dwordx2 v[156:157], v9, s[16:17]
	global_load_dwordx2 v[158:159], v10, s[16:17]
	global_load_dwordx2 v[160:161], v11, s[16:17]
	global_load_dwordx2 v[206:207], v22, s[16:17]
	global_load_dwordx2 v[208:209], v23, s[16:17]
	v_lshlrev_b32_e32 v20, 2, v36
	v_add_u32_e32 v21, 0x5600, v20
	global_load_dwordx4 v[68:71], v20, s[18:19]
	global_load_dwordx4 v[72:75], v20, s[34:35]
	global_load_dwordx4 v[76:79], v20, s[36:37]
	global_load_dwordx4 v[80:83], v20, s[20:21]
	global_load_dwordx4 v[84:87], v21, s[18:19]
	global_load_dwordx4 v[88:91], v21, s[34:35]
	global_load_dwordx4 v[92:95], v21, s[36:37]
	global_load_dwordx4 v[96:99], v21, s[20:21]
	v_lshlrev_b32_e32 v67, 6, v66
	v_mad_u32_u24 v67, v3, 63, v67
	v_mad_u32_u24 v109, v67, s7, v7
	s_movk_i32 s0, 0x1ff
	v_cmp_ne_u32_e64 s[38:39], 0, v104
	v_cmp_ne_u32_e64 s[40:41], s0, v104
	s_waitcnt vmcnt(28)
; __device__ __forceinline__ unsigned cvt_pk_bf16(float lo, float hi) { unsigned r; asm volatile("v_cvt_pk_bf16_f32 %0, %1, %2" : "=v"(r) : "v"(lo), "v"(hi)); return r; }
; __device__ __forceinline__ float sigmoid_f(float x) { return fast_rcp(1.0f + fast_exp2(-1.4426950409f * x)); }
; __device__ __forceinline__ f32x4 raw4(const bf16_t* p) { const u32x2 w = *(const u32x2*)p; return (f32x4){bf_lo(w.x), bf_hi(w.x), bf_lo(w.y), bf_hi(w.y)}; }
; __device__ __forceinline__ void conv_fixup(const bf16_t* RAW, const float* ck, const float* cb, bf16_t* ACT, int gtid, int nthr) {
;     ...
; #pragma unroll
;         for (int bj = 0; bj < 2; ++bj) {
;             const bf16_t* base = RAW + bj * FF + j4;
;             f32x4 pv, cur, nv;
;             if (!last) { pv = grp > 0 ? raw4(base + (size_t)((grp - 1) * 4 + 3) * NUP) : z; cur = raw4(base + (size_t)(grp * 4 + 0) * NUP); nv = raw4(base + (size_t)(grp * 4 + 1) * NUP); }
;             else { pv = raw4(base + (size_t)(grp * 4 + 2) * NUP); cur = raw4(base + (size_t)(grp * 4 + 3) * NUP); nv = grp < 127 ? raw4(base + (size_t)((grp + 1) * 4 + 0) * NUP) : z; }
;             cv[bj] = *(const f32x4*)(ck + 0 * NUP + bj * FF + j4) * pv + *(const f32x4*)(ck + 1 * NUP + bj * FF + j4) * cur + *(const f32x4*)(ck + 2 * NUP + bj * FF + j4) * nv + *(const f32x4*)(cb + bj * FF + j4);
;         }
;         const f32x4 gt = cv[0], vl = cv[1];
;         u32x2 w; w.x = cvt_pk_bf16(gt[0] * sigmoid_f(gt[0]) * vl[0], gt[1] * sigmoid_f(gt[1]) * vl[1]); w.y = cvt_pk_bf16(gt[2] * sigmoid_f(gt[2]) * vl[2], gt[3] * sigmoid_f(gt[3]) * vl[3]);
;         *(u32x2*)(ACT + (size_t)row * FF + j4) = w;
	v_cndmask_b32_e64 v12, 0, v12, s[38:39]
	v_cndmask_b32_e64 v13, 0, v13, s[38:39]
	v_cndmask_b32_e64 v18, 0, v18, s[38:39]
	v_cndmask_b32_e64 v19, 0, v19, s[38:39]
	v_cndmask_b32_e64 v16, 0, v16, s[40:41]
	v_cndmask_b32_e64 v17, 0, v17, s[40:41]
	v_cndmask_b32_e64 v60, 0, v60, s[40:41]
	v_cndmask_b32_e64 v61, 0, v61, s[40:41]
	v_lshlrev_b32_e32 v210, 16, v12
	v_and_b32_e32 v211, 0xffff0000, v12
	v_lshlrev_b32_e32 v212, 16, v13
	v_and_b32_e32 v213, 0xffff0000, v13
	v_lshlrev_b32_e32 v214, 16, v14
	v_and_b32_e32 v215, 0xffff0000, v14
	v_lshlrev_b32_e32 v216, 16, v15
	v_and_b32_e32 v217, 0xffff0000, v15
	v_lshlrev_b32_e32 v218, 16, v16
	v_and_b32_e32 v219, 0xffff0000, v16
	v_lshlrev_b32_e32 v220, 16, v17
	v_and_b32_e32 v221, 0xffff0000, v17
	v_pk_mul_f32 v[224:225], v[28:29], v[214:215]
	v_pk_fma_f32 v[224:225], v[210:211], v[24:25], v[224:225]
	v_pk_fma_f32 v[224:225], v[218:219], v[32:33], v[224:225]
	v_pk_add_f32 v[224:225], v[40:41], v[224:225]
	v_pk_mul_f32 v[226:227], v[30:31], v[216:217]
	v_pk_fma_f32 v[226:227], v[212:213], v[26:27], v[226:227]
	v_pk_fma_f32 v[226:227], v[220:221], v[34:35], v[226:227]
	v_pk_add_f32 v[226:227], v[42:43], v[226:227]
	v_lshlrev_b32_e32 v210, 16, v18
	v_and_b32_e32 v211, 0xffff0000, v18
	v_lshlrev_b32_e32 v212, 16, v19
	v_and_b32_e32 v213, 0xffff0000, v19
	v_lshlrev_b32_e32 v214, 16, v38
	v_and_b32_e32 v215, 0xffff0000, v38
	v_lshlrev_b32_e32 v216, 16, v39
	v_and_b32_e32 v217, 0xffff0000, v39
	v_lshlrev_b32_e32 v218, 16, v60
	v_and_b32_e32 v219, 0xffff0000, v60
	v_lshlrev_b32_e32 v220, 16, v61
	v_and_b32_e32 v221, 0xffff0000, v61
	v_pk_mul_f32 v[228:229], v[48:49], v[214:215]
	v_pk_fma_f32 v[228:229], v[210:211], v[44:45], v[228:229]
	v_pk_fma_f32 v[228:229], v[218:219], v[52:53], v[228:229]
	v_pk_add_f32 v[228:229], v[56:57], v[228:229]
	v_pk_mul_f32 v[230:231], v[50:51], v[216:217]
	v_pk_fma_f32 v[230:231], v[212:213], v[46:47], v[230:231]
	v_pk_fma_f32 v[230:231], v[220:221], v[54:55], v[230:231]
	v_pk_add_f32 v[230:231], v[58:59], v[230:231]
	v_mul_f32_e32 v100, 0xbfb8aa3b, v224
	v_exp_f32_e32 v100, v100
	v_mul_f32_e32 v101, 0xbfb8aa3b, v225
	v_exp_f32_e32 v101, v101
	v_mul_f32_e32 v102, 0xbfb8aa3b, v226
	v_exp_f32_e32 v102, v102
	v_mul_f32_e32 v103, 0xbfb8aa3b, v227
	v_exp_f32_e32 v103, v103
	s_nop 0
	v_add_f32_e32 v100, 1.0, v100
	v_rcp_f32_e32 v100, v100
	v_add_f32_e32 v101, 1.0, v101
	v_rcp_f32_e32 v101, v101
	v_add_f32_e32 v102, 1.0, v102
	v_rcp_f32_e32 v102, v102
	v_add_f32_e32 v103, 1.0, v103
	v_rcp_f32_e32 v103, v103
	s_nop 0
	v_mul_f32_e32 v100, v224, v100
	v_mul_f32_e32 v100, v100, v228
	v_mul_f32_e32 v101, v225, v101
	v_mul_f32_e32 v101, v101, v229
	v_mul_f32_e32 v102, v226, v102
	v_mul_f32_e32 v102, v102, v230
	v_mul_f32_e32 v103, v227, v103
	v_mul_f32_e32 v103, v103, v231
	v_cvt_pk_bf16_f32 v2, v100, v101
	v_cvt_pk_bf16_f32 v3, v102, v103
	global_store_dwordx2 v107, v[2:3], s[30:31]
	s_movk_i32 s0, 0x1ff
	v_cmp_ne_u32_e64 s[38:39], 0, v105
	v_cmp_ne_u32_e64 s[40:41], s0, v105
	s_waitcnt vmcnt(14)
	v_cndmask_b32_e64 v142, 0, v142, s[38:39]
	v_cndmask_b32_e64 v143, 0, v143, s[38:39]
	v_cndmask_b32_e64 v148, 0, v148, s[38:39]
	v_cndmask_b32_e64 v149, 0, v149, s[38:39]
	v_cndmask_b32_e64 v146, 0, v146, s[40:41]
	v_cndmask_b32_e64 v147, 0, v147, s[40:41]
	v_cndmask_b32_e64 v152, 0, v152, s[40:41]
	v_cndmask_b32_e64 v153, 0, v153, s[40:41]
	v_lshlrev_b32_e32 v210, 16, v142
	v_and_b32_e32 v211, 0xffff0000, v142
	v_lshlrev_b32_e32 v212, 16, v143
	v_and_b32_e32 v213, 0xffff0000, v143
	v_lshlrev_b32_e32 v214, 16, v144
	v_and_b32_e32 v215, 0xffff0000, v144
	v_lshlrev_b32_e32 v216, 16, v145
	v_and_b32_e32 v217, 0xffff0000, v145
	v_lshlrev_b32_e32 v218, 16, v146
	v_and_b32_e32 v219, 0xffff0000, v146
	v_lshlrev_b32_e32 v220, 16, v147
	v_and_b32_e32 v221, 0xffff0000, v147
	v_pk_mul_f32 v[224:225], v[178:179], v[214:215]
	v_pk_fma_f32 v[224:225], v[210:211], v[174:175], v[224:225]
	v_pk_fma_f32 v[224:225], v[218:219], v[182:183], v[224:225]
	v_pk_add_f32 v[224:225], v[186:187], v[224:225]
	v_pk_mul_f32 v[226:227], v[180:181], v[216:217]
	v_pk_fma_f32 v[226:227], v[212:213], v[176:177], v[226:227]
	v_pk_fma_f32 v[226:227], v[220:221], v[184:185], v[226:227]
	v_pk_add_f32 v[226:227], v[188:189], v[226:227]
	v_lshlrev_b32_e32 v210, 16, v148
	v_and_b32_e32 v211, 0xffff0000, v148
	v_lshlrev_b32_e32 v212, 16, v149
	v_and_b32_e32 v213, 0xffff0000, v149
	v_lshlrev_b32_e32 v214, 16, v150
	v_and_b32_e32 v215, 0xffff0000, v150
	v_lshlrev_b32_e32 v216, 16, v151
	v_and_b32_e32 v217, 0xffff0000, v151
	v_lshlrev_b32_e32 v218, 16, v152
	v_and_b32_e32 v219, 0xffff0000, v152
	v_lshlrev_b32_e32 v220, 16, v153
	v_and_b32_e32 v221, 0xffff0000, v153
	v_pk_mul_f32 v[228:229], v[194:195], v[214:215]
	v_pk_fma_f32 v[228:229], v[210:211], v[190:191], v[228:229]
	v_pk_fma_f32 v[228:229], v[218:219], v[198:199], v[228:229]
	v_pk_add_f32 v[228:229], v[202:203], v[228:229]
	v_pk_mul_f32 v[230:231], v[196:197], v[216:217]
	v_pk_fma_f32 v[230:231], v[212:213], v[192:193], v[230:231]
	v_pk_fma_f32 v[230:231], v[220:221], v[200:201], v[230:231]
	v_pk_add_f32 v[230:231], v[204:205], v[230:231]
	v_mul_f32_e32 v100, 0xbfb8aa3b, v224
	v_exp_f32_e32 v100, v100
	v_mul_f32_e32 v101, 0xbfb8aa3b, v225
	v_exp_f32_e32 v101, v101
	v_mul_f32_e32 v102, 0xbfb8aa3b, v226
	v_exp_f32_e32 v102, v102
	v_mul_f32_e32 v103, 0xbfb8aa3b, v227
	v_exp_f32_e32 v103, v103
	s_nop 0
	v_add_f32_e32 v100, 1.0, v100
	v_rcp_f32_e32 v100, v100
	v_add_f32_e32 v101, 1.0, v101
	v_rcp_f32_e32 v101, v101
	v_add_f32_e32 v102, 1.0, v102
	v_rcp_f32_e32 v102, v102
	v_add_f32_e32 v103, 1.0, v103
	v_rcp_f32_e32 v103, v103
	s_nop 0
	v_mul_f32_e32 v100, v224, v100
	v_mul_f32_e32 v100, v100, v228
	v_mul_f32_e32 v101, v225, v101
	v_mul_f32_e32 v101, v101, v229
	v_mul_f32_e32 v102, v226, v102
	v_mul_f32_e32 v102, v102, v230
	v_mul_f32_e32 v103, v227, v103
	v_mul_f32_e32 v103, v103, v231
	v_cvt_pk_bf16_f32 v2, v100, v101
	v_cvt_pk_bf16_f32 v3, v102, v103
	s_and_saveexec_b64 s[40:41], s[44:45]
	global_store_dwordx2 v108, v[2:3], s[30:31]
	s_mov_b64 exec, s[40:41]
	s_movk_i32 s0, 0x1ff
	v_cmp_ne_u32_e64 s[38:39], 0, v106
	v_cmp_ne_u32_e64 s[40:41], s0, v106
	s_waitcnt vmcnt(0)
; __device__ __forceinline__ unsigned cvt_pk_bf16(float lo, float hi) { unsigned r; asm volatile("v_cvt_pk_bf16_f32 %0, %1, %2" : "=v"(r) : "v"(lo), "v"(hi)); return r; }
; __device__ __forceinline__ float sigmoid_f(float x) { return fast_rcp(1.0f + fast_exp2(-1.4426950409f * x)); }
; __device__ __forceinline__ f32x4 raw4(const bf16_t* p) { const u32x2 w = *(const u32x2*)p; return (f32x4){bf_lo(w.x), bf_hi(w.x), bf_lo(w.y), bf_hi(w.y)}; }
; __device__ __forceinline__ void conv_fixup(const bf16_t* RAW, const float* ck, const float* cb, bf16_t* ACT, int gtid, int nthr) {
;     ...
;     for (int task = gtid; task < NTASK; task += nthr) {
;     ...
; #pragma unroll
;         for (int bj = 0; bj < 2; ++bj) {
;             const bf16_t* base = RAW + bj * FF + j4;
;             f32x4 pv, cur, nv;
;             if (!last) { pv = grp > 0 ? raw4(base + (size_t)((grp - 1) * 4 + 3) * NUP) : z; cur = raw4(base + (size_t)(grp * 4 + 0) * NUP); nv = raw4(base + (size_t)(grp * 4 + 1) * NUP); }
;             else { pv = raw4(base + (size_t)(grp * 4 + 2) * NUP); cur = raw4(base + (size_t)(grp * 4 + 3) * NUP); nv = grp < 127 ? raw4(base + (size_t)((grp + 1) * 4 + 0) * NUP) : z; }
;             cv[bj] = *(const f32x4*)(ck + 0 * NUP + bj * FF + j4) * pv + *(const f32x4*)(ck + 1 * NUP + bj * FF + j4) * cur + *(const f32x4*)(ck + 2 * NUP + bj * FF + j4) * nv + *(const f32x4*)(cb + bj * FF + j4);
;         }
;         const f32x4 gt = cv[0], vl = cv[1];
;         u32x2 w; w.x = cvt_pk_bf16(gt[0] * sigmoid_f(gt[0]) * vl[0], gt[1] * sigmoid_f(gt[1]) * vl[1]); w.y = cvt_pk_bf16(gt[2] * sigmoid_f(gt[2]) * vl[2], gt[3] * sigmoid_f(gt[3]) * vl[3]);
;         *(u32x2*)(ACT + (size_t)row * FF + j4) = w;
	v_cndmask_b32_e64 v154, 0, v154, s[38:39]
	v_cndmask_b32_e64 v155, 0, v155, s[38:39]
	v_cndmask_b32_e64 v160, 0, v160, s[38:39]
	v_cndmask_b32_e64 v161, 0, v161, s[38:39]
	v_cndmask_b32_e64 v158, 0, v158, s[40:41]
	v_cndmask_b32_e64 v159, 0, v159, s[40:41]
	v_cndmask_b32_e64 v208, 0, v208, s[40:41]
	v_cndmask_b32_e64 v209, 0, v209, s[40:41]
	v_lshlrev_b32_e32 v210, 16, v154
	v_and_b32_e32 v211, 0xffff0000, v154
	v_lshlrev_b32_e32 v212, 16, v155
	v_and_b32_e32 v213, 0xffff0000, v155
	v_lshlrev_b32_e32 v214, 16, v156
	v_and_b32_e32 v215, 0xffff0000, v156
	v_lshlrev_b32_e32 v216, 16, v157
	v_and_b32_e32 v217, 0xffff0000, v157
	v_lshlrev_b32_e32 v218, 16, v158
	v_and_b32_e32 v219, 0xffff0000, v158
	v_lshlrev_b32_e32 v220, 16, v159
	v_and_b32_e32 v221, 0xffff0000, v159
	v_pk_mul_f32 v[224:225], v[72:73], v[214:215]
	v_pk_fma_f32 v[224:225], v[210:211], v[68:69], v[224:225]
	v_pk_fma_f32 v[224:225], v[218:219], v[76:77], v[224:225]
	v_pk_add_f32 v[224:225], v[80:81], v[224:225]
	v_pk_mul_f32 v[226:227], v[74:75], v[216:217]
	v_pk_fma_f32 v[226:227], v[212:213], v[70:71], v[226:227]
	v_pk_fma_f32 v[226:227], v[220:221], v[78:79], v[226:227]
	v_pk_add_f32 v[226:227], v[82:83], v[226:227]
	v_lshlrev_b32_e32 v210, 16, v160
	v_and_b32_e32 v211, 0xffff0000, v160
	v_lshlrev_b32_e32 v212, 16, v161
	v_and_b32_e32 v213, 0xffff0000, v161
	v_lshlrev_b32_e32 v214, 16, v206
	v_and_b32_e32 v215, 0xffff0000, v206
	v_lshlrev_b32_e32 v216, 16, v207
	v_and_b32_e32 v217, 0xffff0000, v207
	v_lshlrev_b32_e32 v218, 16, v208
	v_and_b32_e32 v219, 0xffff0000, v208
	v_lshlrev_b32_e32 v220, 16, v209
	v_and_b32_e32 v221, 0xffff0000, v209
	v_pk_mul_f32 v[228:229], v[88:89], v[214:215]
	v_pk_fma_f32 v[228:229], v[210:211], v[84:85], v[228:229]
	v_pk_fma_f32 v[228:229], v[218:219], v[92:93], v[228:229]
	v_pk_add_f32 v[228:229], v[96:97], v[228:229]
	v_pk_mul_f32 v[230:231], v[90:91], v[216:217]
	v_pk_fma_f32 v[230:231], v[212:213], v[86:87], v[230:231]
	v_pk_fma_f32 v[230:231], v[220:221], v[94:95], v[230:231]
	v_pk_add_f32 v[230:231], v[98:99], v[230:231]
	v_mul_f32_e32 v100, 0xbfb8aa3b, v224
	v_exp_f32_e32 v100, v100
	v_mul_f32_e32 v101, 0xbfb8aa3b, v225
	v_exp_f32_e32 v101, v101
	v_mul_f32_e32 v102, 0xbfb8aa3b, v226
	v_exp_f32_e32 v102, v102
	v_mul_f32_e32 v103, 0xbfb8aa3b, v227
	v_exp_f32_e32 v103, v103
	s_nop 0
	v_add_f32_e32 v100, 1.0, v100
	v_rcp_f32_e32 v100, v100
	v_add_f32_e32 v101, 1.0, v101
	v_rcp_f32_e32 v101, v101
	v_add_f32_e32 v102, 1.0, v102
	v_rcp_f32_e32 v102, v102
	v_add_f32_e32 v103, 1.0, v103
	v_rcp_f32_e32 v103, v103
	s_nop 0
	v_mul_f32_e32 v100, v224, v100
	v_mul_f32_e32 v100, v100, v228
	v_mul_f32_e32 v101, v225, v101
	v_mul_f32_e32 v101, v101, v229
	v_mul_f32_e32 v102, v226, v102
	v_mul_f32_e32 v102, v102, v230
	v_mul_f32_e32 v103, v227, v103
	v_mul_f32_e32 v103, v103, v231
	v_cvt_pk_bf16_f32 v2, v100, v101
	v_cvt_pk_bf16_f32 v3, v102, v103
	s_and_saveexec_b64 s[40:41], s[46:47]
	global_store_dwordx2 v109, v[2:3], s[30:31]
	s_mov_b64 exec, s[40:41]
	s_mul_i32 s0, s80, 3
	v_add_u32_e32 v64, s0, v64
	s_mov_b32 s0, 0x55fff
	v_cmp_lt_i32_e32 vcc, s0, v64
	s_nop 1
	s_or_b64 s[42:43], vcc, s[42:43]
	s_andn2_b64 exec, exec, s[42:43]
	s_cbranch_execz .LBB0_887
